# M1: conv4 z-row loads issued at the start of the workgroup's s5+lru item (one S5 pass earlier)
# speedup vs baseline: 1.0079x; 1.0040x over previous
; template <bool FULL> __device__ __forceinline__ void lru_tile(const Args& a, int l, int tile, LAS unsigned char* lds, int tid, int lane, int wave) {
;     ...
;     for (int it = 0; it < 4; ++it) {
;         const int ch = it * NTHR + tid, t = ch >> 5, c8 = ch & 31;
;         float xc[8];
;         { const f32x4 b0 = *(const f32x4*)(a.in[20] + (size_t)l * 256 + c8 * 8), b1 = *(const f32x4*)(a.in[20] + (size_t)l * 256 + c8 * 8 + 4);
;           xc[0] = b0.x; xc[1] = b0.y; xc[2] = b0.z; xc[3] = b0.w; xc[4] = b1.x; xc[5] = b1.y; xc[6] = b1.z; xc[7] = b1.w; }
; #pragma unroll
;         for (int j = 0; j < 4; ++j) {
;             if (tloc0 + t + j - 3 >= 0) {
;                 const u32x4 v = *(const u32x4*)(Z + (size_t)(t0 + t + j - 3) * IW + 2304 + c8 * 8); float f[8]; unpack8(v, f);
; __global__ void __launch_bounds__(NTHR, 2) fwd_kernel(Args a) {
;     ...
;                 for (int it = blockIdx.x; it < 768; it += G) { PH_IDS
;                     const int bx = it & 255, s = it >> 8, xq = bx & 7, jq = bx >> 3;
;                     if (it < 256) { const int tile = (G == 256) ? xq * 32 + jq : it; s5_m1(a, l, tile, lds, tid, lane, wave); lru_tile<false>(a, l, tile, lds, tid, lane, wave); }
.LBB0_1264:
	s_and_b64 vcc, exec, s[0:1]
	s_cbranch_vccz .LBB0_1257
	s_lshl_b32 s0, s6, 5
	s_and_b32 s0, s0, 0xe0
	s_or_b32 s4, s0, s24
	v_readlane_b32 s0, v251, 16
	v_readlane_b32 s1, v251, 17
	s_and_b64 s[0:1], s[0:1], exec
	s_cselect_b32 s38, s4, s6
	v_and_b32_e32 v77, 15, v76
	s_lshl_b32 s24, s38, 6
	v_ashrrev_i32_e32 v186, 5, v76
	s_add_i32 s98, s24, -3
	v_add_u32_e32 v186, s98, v186
	v_lshlrev_b32_e32 v188, 4, v76
	v_and_b32_e32 v188, 0x1f0, v188
	v_mov_b32_e32 v189, 0
	v_mov_b64_e32 v[190:191], s[20:21]
	s_nop 0
	v_mad_i64_i32 v[190:191], s[98:99], v186, s84, v[190:191]
	s_mov_b32 s98, 0xd601200
	s_mov_b32 s99, 0
	v_lshl_add_u64 v[190:191], v[190:191], 0, v[188:189]
	v_lshl_add_u64 v[190:191], v[190:191], 0, s[98:99]
	s_movk_i32 s98, 0x1600
	global_load_dwordx4 v[198:201], v[190:191], off
	v_lshl_add_u64 v[190:191], v[190:191], 0, s[98:99]
	global_load_dwordx4 v[202:205], v[190:191], off
	v_lshl_add_u64 v[190:191], v[190:191], 0, s[98:99]
	global_load_dwordx4 v[206:209], v[190:191], off
	v_lshl_add_u64 v[190:191], v[190:191], 0, s[98:99]
	global_load_dwordx4 v[210:213], v[190:191], off
	s_mov_b32 s98, 0x11e00
	v_lshl_add_u64 v[190:191], v[190:191], 0, s[98:99]
	s_movk_i32 s98, 0x1600
	global_load_dwordx4 v[214:217], v[190:191], off
	v_lshl_add_u64 v[190:191], v[190:191], 0, s[98:99]
	global_load_dwordx4 v[218:221], v[190:191], off
	v_lshl_add_u64 v[190:191], v[190:191], 0, s[98:99]
	global_load_dwordx4 v[222:225], v[190:191], off
	v_lshl_add_u64 v[190:191], v[190:191], 0, s[98:99]
	global_load_dwordx4 v[226:229], v[190:191], off
	s_mov_b32 s98, 0x11e00
	v_lshl_add_u64 v[190:191], v[190:191], 0, s[98:99]
	s_movk_i32 s98, 0x1600
	global_load_dwordx4 v[230:233], v[190:191], off
	v_lshl_add_u64 v[190:191], v[190:191], 0, s[98:99]
	global_load_dwordx4 v[234:237], v[190:191], off
	v_lshl_add_u64 v[190:191], v[190:191], 0, s[98:99]
	global_load_dwordx4 v[238:241], v[190:191], off
	v_lshl_add_u64 v[190:191], v[190:191], 0, s[98:99]
	global_load_dwordx4 v[242:245], v[190:191], off
	s_mov_b32 s98, 0x11e00
	v_lshl_add_u64 v[190:191], v[190:191], 0, s[98:99]
	s_movk_i32 s98, 0x1600
	global_load_dwordx4 v[246:249], v[190:191], off
	v_lshl_add_u64 v[190:191], v[190:191], 0, s[98:99]
	global_load_dwordx4 v[150:153], v[190:191], off
	v_lshl_add_u64 v[190:191], v[190:191], 0, s[98:99]
	global_load_dwordx4 v[154:157], v[190:191], off
	v_lshl_add_u64 v[190:191], v[190:191], 0, s[98:99]
	global_load_dwordx4 v[158:161], v[190:191], off
	v_or_b32_e32 v67, s24, v77
	v_or_b32_e32 v2, 16, v67
	v_mad_i64_i32 v[50:51], s[0:1], v2, s84, 0
	v_or_b32_e32 v2, 32, v67
	v_mad_i64_i32 v[52:53], s[0:1], v2, s84, 0
	v_or_b32_e32 v2, 48, v67
	v_mad_i64_i32 v[48:49], s[0:1], v67, s84, 0
	v_mad_i64_i32 v[54:55], s[0:1], v2, s84, 0
	v_readlane_b32 s0, v254, 33
	v_lshlrev_b32_e32 v144, 2, v66
	v_readlane_b32 s1, v254, 34
	s_lshl_b32 s25, s26, 1
	s_mulk_i32 s26, 0x2100
	v_lshl_add_u64 v[56:57], s[0:1], 0, v[144:145]
	v_readlane_b32 s0, v254, 35
	v_and_b32_e32 v78, 48, v76
	v_mov_b32_e32 v79, v145
	v_readlane_b32 s1, v254, 36
	s_add_i32 s4, s26, 0
	v_mul_u32_u24_e32 v0, 0x210, v77
	v_lshl_add_u64 v[58:59], s[0:1], 0, v[78:79]
	v_readlane_b32 s0, v252, 50
	v_add_u32_e32 v1, s4, v78
	v_readlane_b32 s1, v252, 51
	v_cmp_gt_u32_e64 s[36:37], 32, v66
	v_add_u32_e32 v68, s4, v144
	s_lshl_b32 s26, s38, 4
	v_lshl_add_u64 v[60:61], s[8:9], 0, v[78:79]
	v_lshl_add_u64 v[62:63], s[0:1], 0, v[144:145]
	s_mov_b32 s0, 0
	s_mov_b64 s[4:5], -1
	v_add_u32_e32 v69, v1, v0
	s_branch .LBB0_1267

; template <bool FULL> __device__ __forceinline__ void lru_tile(const Args& a, int l, int tile, LAS unsigned char* lds, int tid, int lane, int wave) {
;     ...
;     for (int it = 0; it < 4; ++it) {
;         const int ch = it * NTHR + tid, t = ch >> 5, c8 = ch & 31;
;         float xc[8];
;         { const f32x4 b0 = *(const f32x4*)(a.in[20] + (size_t)l * 256 + c8 * 8), b1 = *(const f32x4*)(a.in[20] + (size_t)l * 256 + c8 * 8 + 4);
;           xc[0] = b0.x; xc[1] = b0.y; xc[2] = b0.z; xc[3] = b0.w; xc[4] = b1.x; xc[5] = b1.y; xc[6] = b1.z; xc[7] = b1.w; }
; #pragma unroll
;         for (int j = 0; j < 4; ++j) {
;             if (tloc0 + t + j - 3 >= 0) {
;                 const u32x4 v = *(const u32x4*)(Z + (size_t)(t0 + t + j - 3) * IW + 2304 + c8 * 8); float f[8]; unpack8(v, f);
;                 const f32x4 w0 = *(const f32x4*)(a.in[19] + ((size_t)l * 4 + j) * 256 + c8 * 8), w1 = *(const f32x4*)(a.in[19] + ((size_t)l * 4 + j) * 256 + c8 * 8 + 4);
;                 xc[0] = fmaf(w0.x, f[0], xc[0]); xc[1] = fmaf(w0.y, f[1], xc[1]); xc[2] = fmaf(w0.z, f[2], xc[2]); xc[3] = fmaf(w0.w, f[3], xc[3]);
;                 xc[4] = fmaf(w1.x, f[4], xc[4]); xc[5] = fmaf(w1.y, f[5], xc[5]); xc[6] = fmaf(w1.z, f[6], xc[6]); xc[7] = fmaf(w1.w, f[7], xc[7]);
;             }
.LBB0_1291:
	v_lshlrev_b32_e32 v0, 3, v76
	v_and_b32_e32 v8, 0xf8, v0
	v_readlane_b32 s0, v254, 37
	v_lshlrev_b32_e32 v144, 2, v8
	v_readlane_b32 s1, v254, 38
	s_barrier
	s_nop 3
	global_load_dwordx4 v[0:3], v144, s[0:1] offset:16
	global_load_dwordx4 v[4:7], v144, s[0:1]
	s_and_b32 s4, s24, 0x1fc0
	v_ashrrev_i32_e32 v9, 5, v76
	v_readlane_b32 s0, v254, 39
	s_add_i32 s5, s24, -3
	v_add_u32_e32 v14, s4, v9
	v_readlane_b32 s1, v254, 40
	v_add_u32_e32 v15, s5, v9
	v_cmp_lt_i32_e32 vcc, 2, v14
	v_lshl_add_u64 v[10:11], s[0:1], 0, v[144:145]
	v_lshlrev_b32_e32 v12, 1, v8
	s_and_saveexec_b64 s[0:1], vcc
	s_cbranch_execz .LBB0_1295
	v_mov_b64_e32 v[16:17], s[20:21]
	v_mad_i64_i32 v[16:17], s[26:27], v15, s84, v[16:17]
	v_mov_b32_e32 v13, v145
	v_lshl_add_u64 v[16:17], v[16:17], 0, v[12:13]
	v_add_co_u32_e32 v16, vcc, 0xd601000, v16
	s_nop 1
	v_addc_co_u32_e32 v17, vcc, 0, v17, vcc
	s_waitcnt vmcnt(0)
	v_lshlrev_b32_e32 v24, 16, v198
	v_and_b32_e32 v25, 0xffff0000, v198
	v_lshlrev_b32_e32 v26, 16, v199
	v_and_b32_e32 v27, 0xffff0000, v199
	v_lshlrev_b32_e32 v28, 16, v200
	v_and_b32_e32 v29, 0xffff0000, v200
	v_lshlrev_b32_e32 v30, 16, v201
	v_and_b32_e32 v31, 0xffff0000, v201
	global_load_dwordx4 v[16:19], v[10:11], off offset:16
	global_load_dwordx4 v[20:23], v[10:11], off
	s_waitcnt vmcnt(1)
	v_pk_fma_f32 v[0:1], v[16:17], v[28:29], v[0:1]
	s_waitcnt vmcnt(0)
	v_pk_fma_f32 v[4:5], v[20:21], v[24:25], v[4:5]
	v_pk_fma_f32 v[6:7], v[22:23], v[26:27], v[6:7]
	v_pk_fma_f32 v[2:3], v[18:19], v[30:31], v[2:3]
	s_or_b64 exec, exec, s[0:1]
	v_cmp_lt_i32_e32 vcc, 1, v14
	s_and_saveexec_b64 s[0:1], vcc
	s_cbranch_execnz .LBB0_1296
